# layer-0 context-row out/down projections moved out of the 256x256 GEMM tile loop (which had a second round on 8 workgroups) into a balanced 64x32-per-workgroup MFMA mini-GEMM with K split over the 8 w
# speedup vs baseline: 1.0935x; 1.0345x over previous
.LBB0_681:
	s_or_b64 exec, exec, s[0:1]
	v_readlane_b32 s0, v254, 43
	v_readlane_b32 s1, v254, 44
	s_and_b64 s[0:1], exec, s[0:1]
	s_mov_b32 s56, 64
	v_readlane_b32 s0, v252, 43
	s_lshl_b32 s0, s56, 2
	s_cmp_lt_i32 s63, s0
	v_readlane_b32 s1, v252, 44
	s_cselect_b64 s[52:53], -1, 0
	s_lshr_b32 s73, s56, 1
	s_mov_b64 s[64:65], s[0:1]
	s_cmp_ge_i32 s63, s0
	s_waitcnt lgkmcnt(0)
	s_barrier
	v_mbcnt_lo_u32_b32 v14, -1, 0
	v_mbcnt_hi_u32_b32 v14, -1, v14
	s_cbranch_scc1 .LBB0_697
	v_lshl_add_u32 v0, v14, 4, s33
	v_add_u32_e32 v1, 0x2000, v0
	v_ashrrev_i32_e32 v2, 31, v1
	v_lshrrev_b32_e32 v2, 22, v2
	v_add_u32_e32 v2, v1, v2
	v_ashrrev_i32_e32 v8, 10, v2
	v_mul_i32_i24_e32 v3, 0x400, v8
	v_sub_u32_e32 v1, v1, v3
	v_lshrrev_b32_e32 v3, 4, v1
	v_bitop3_b32 v1, v3, v1, 32 bitop3:0x6c
	v_ashrrev_i32_e32 v3, 31, v1
	v_lshrrev_b32_e32 v3, 26, v3
	v_add_u32_e32 v3, v1, v3
	v_ashrrev_i32_e32 v9, 6, v3
	v_and_b32_e32 v3, 0xffc0, v3
	v_sub_u32_e32 v1, v1, v3
	v_lshrrev_b16_e32 v3, 7, v1
	v_and_b32_e32 v3, 1, v3
	v_add_u16_e32 v1, v1, v3
	v_lshlrev_b32_e32 v2, 5, v8
	v_ashrrev_i16_sdwa v1, v250, sext(v1) dst_sel:DWORD dst_unused:UNUSED_PAD src0_sel:DWORD src1_sel:BYTE_0
	v_and_b32_e32 v2, 32, v2
	v_bfe_i32 v10, v1, 0, 16
	v_add_u32_e32 v1, v2, v10
	v_lshlrev_b32_e32 v2, 3, v8
	v_and_b32_e32 v2, 0x1ffff0, v2
	v_add_lshl_u32 v2, v9, v2, 11
	v_lshl_add_u32 v144, v1, 1, v2
	v_ashrrev_i32_e32 v1, 31, v0
	v_lshrrev_b32_e32 v1, 22, v1
	v_add_u32_e32 v1, v0, v1
	v_ashrrev_i32_e32 v11, 10, v1
	v_readlane_b32 s0, v254, 61
	v_mul_i32_i24_e32 v2, 0x400, v11
	s_add_u32 s22, s0, 0x580000
	v_readlane_b32 s0, v254, 62
	v_sub_u32_e32 v0, v0, v2
	s_addc_u32 s23, s0, 0
	v_lshrrev_b32_e32 v2, 4, v0
	v_readlane_b32 s0, v253, 50
	v_bitop3_b32 v0, v2, v0, 32 bitop3:0x6c
	s_add_i32 s0, s73, s0
	v_readlane_b32 s1, v253, 49
	v_ashrrev_i32_e32 v2, 31, v0
	s_mul_i32 s0, s0, s1
	v_readlane_b32 s1, v253, 48
	v_lshrrev_b32_e32 v2, 26, v2
	s_add_i32 s0, s0, s1
	v_add_u32_e32 v2, v0, v2
	s_ashr_i32 s1, s0, 31
	v_ashrrev_i32_e32 v12, 6, v2
	v_and_b32_e32 v2, 0xc0, v2
	s_lshr_b32 s1, s1, 27
	v_sub_u32_e32 v0, v0, v2
	s_add_i32 s1, s0, s1
	v_lshlrev_b32_e32 v1, 5, v11
	v_ashrrev_i16_sdwa v0, v250, sext(v0) dst_sel:DWORD dst_unused:UNUSED_PAD src0_sel:DWORD src1_sel:BYTE_0
	s_ashr_i32 s4, s1, 5
	v_and_b32_e32 v1, 32, v1
	v_bfe_i32 v13, v0, 0, 16
	s_lshl_b32 s4, s4, 3
	v_add_u32_e32 v0, v1, v13
	v_lshlrev_b32_e32 v1, 3, v11
	s_sub_i32 s5, s56, s4
	v_and_b32_e32 v1, 0x1ffff0, v1
	s_min_i32 s5, s5, 8
	v_add_lshl_u32 v1, v12, v1, 11
	s_sext_i32_i8 s6, s5
	v_lshl_add_u32 v160, v0, 1, v1
	v_cvt_f32_i32_e32 v0, s6
	s_andn2_b32 s1, s1, 31
	s_sub_i32 s7, s0, s1
	v_cvt_f32_i32_e32 v1, s7
	v_rcp_iflag_f32_e32 v2, v0
	s_xor_b32 s0, s7, s6
	s_ashr_i32 s0, s0, 30
	s_or_b32 s6, s0, 1
	v_mul_f32_e32 v2, v1, v2
	v_trunc_f32_e32 v2, v2
	v_fma_f32 v1, -v2, v0, v1
	v_cvt_i32_f32_e32 v2, v2
	v_cmp_ge_f32_e64 s[0:1], |v1|, |v0|
	s_and_b64 s[0:1], s[0:1], exec
	s_cselect_b32 s0, s6, 0
	v_readfirstlane_b32 s1, v2
	s_add_i32 s0, s1, s0
	s_mul_i32 s1, s0, s5
	s_sub_i32 s1, s7, s1
	s_sext_i32_i8 s1, s1
	s_add_i32 s12, s4, s1
	s_ashr_i32 s13, s12, 31
	s_bfe_i64 s[6:7], s[0:1], 0x80000
	s_lshl_b64 s[4:5], s[12:13], 19
	s_lshl_b64 s[6:7], s[6:7], 19
	s_add_u32 s16, s22, s6
	s_addc_u32 s17, s23, s7
	s_add_i32 s13, s33, 0
	s_add_i32 m0, s13, 0x10000
	v_readlane_b32 s6, v255, 5
	global_load_lds_dwordx4 v160, s[16:17]
	s_add_i32 m0, s13, 0x12000
	v_readlane_b32 s7, v255, 6
	s_add_u32 s14, s6, s4
	s_addc_u32 s15, s7, s5
	s_add_u32 s4, s16, 0x40000
	global_load_lds_dwordx4 v144, s[16:17]
	s_addc_u32 s5, s17, 0
	s_add_i32 m0, s13, 0x14000
	s_add_i32 s24, s13, 0x2000
	global_load_lds_dwordx4 v160, s[4:5]
	s_add_i32 m0, s13, 0x16000
	v_mov_b32_e32 v145, v161
	global_load_lds_dwordx4 v144, s[4:5]
	s_mov_b32 m0, s13
	s_add_u32 s4, s14, 0x40000
	global_load_lds_dwordx4 v160, s[14:15]
	s_mov_b32 m0, s24
	s_addc_u32 s5, s15, 0
	s_add_i32 s25, s13, 0x4000
	global_load_lds_dwordx4 v144, s[14:15]
	s_mov_b32 m0, s25
	s_add_i32 s26, s13, 0x6000
	global_load_lds_dwordx4 v160, s[4:5]
	s_mov_b32 m0, s26
	v_lshl_add_u64 v[6:7], s[16:17], 0, v[160:161]
	global_load_lds_dwordx4 v144, s[4:5]
	v_lshl_add_u64 v[4:5], s[16:17], 0, v[144:145]
	v_lshl_add_u64 v[2:3], s[14:15], 0, v[160:161]
	s_and_b64 vcc, exec, s[76:77]
	v_lshl_add_u64 v[0:1], s[14:15], 0, v[144:145]
	s_cbranch_vccnz .LBB0_684
	s_barrier

.LBB0_697:
	v_writelane_b32 v248, s0, 0
	v_writelane_b32 v248, s1, 1
	v_writelane_b32 v248, s2, 2
	v_writelane_b32 v248, s3, 3
	v_writelane_b32 v248, s4, 4
	v_writelane_b32 v248, s5, 5
	v_writelane_b32 v248, s6, 6
	v_writelane_b32 v248, s7, 7
	v_writelane_b32 v248, s8, 8
	v_writelane_b32 v248, s9, 9
	v_writelane_b32 v248, s10, 10
	v_writelane_b32 v248, s11, 11
	v_writelane_b32 v248, s12, 12
	v_writelane_b32 v248, s13, 13
	v_writelane_b32 v248, s14, 14
	v_writelane_b32 v248, s15, 15
	v_writelane_b32 v248, s16, 16
	v_writelane_b32 v248, s17, 17
	v_writelane_b32 v248, s18, 18
	v_writelane_b32 v248, s19, 19
	v_writelane_b32 v248, s20, 20
	v_writelane_b32 v248, s21, 21
	v_writelane_b32 v248, s22, 22
	v_writelane_b32 v248, s23, 23
	v_writelane_b32 v248, s24, 24
	v_writelane_b32 v248, s25, 25
	v_writelane_b32 v248, s26, 26
	v_writelane_b32 v248, s27, 27
	v_readlane_b32 s0, v254, 38
	v_readlane_b32 s2, v251, 18
	v_readlane_b32 s3, v251, 19
	v_readlane_b32 s4, v251, 44
	s_cmp_lg_u32 s0, 0
	s_cbranch_scc1 .Lcg_pd_done
	s_lshr_b32 s4, s4, 6
	s_lshr_b32 s5, s63, 5
	s_and_b32 s6, s63, 31
	s_lshl_b32 s5, s5, 6
	s_lshl_b32 s6, s6, 5
	v_mbcnt_lo_u32_b32 v140, -1, 0
	v_mbcnt_hi_u32_b32 v140, -1, v140
	v_and_b32_e32 v141, 31, v140
	v_lshrrev_b32_e32 v142, 5, v140
	s_mul_i32 s7, s4, 256
	v_lshl_add_u32 v143, v142, 5, s7
	v_add_u32_e32 v144, s5, v141
	v_mul_u32_u24_e32 v144, 2048, v144
	v_add_u32_e32 v144, v144, v143
	v_mov_b32_e32 v145, 0
	s_add_u32 s8, s2, 0xe100000
	s_addc_u32 s9, s3, 0
	v_lshl_add_u64 v[146:147], s[8:9], 0, v[144:145]
	s_mov_b64 s[10:11], 0x10000
	v_lshl_add_u64 v[148:149], v[146:147], 0, s[10:11]
	v_add_u32_e32 v144, s6, v141
	v_mul_u32_u24_e32 v144, 2048, v144
	v_add_u32_e32 v144, v144, v143
	s_add_u32 s8, s2, 0x680000
	s_addc_u32 s9, s3, 0
	v_lshl_add_u64 v[150:151], s[8:9], 0, v[144:145]
	v_mov_b32_e32 v0, 0
	v_mov_b32_e32 v1, 0
	v_mov_b32_e32 v2, 0
	v_mov_b32_e32 v3, 0
	v_mov_b32_e32 v4, 0
	v_mov_b32_e32 v5, 0
	v_mov_b32_e32 v6, 0
	v_mov_b32_e32 v7, 0
	v_mov_b32_e32 v8, 0
	v_mov_b32_e32 v9, 0
	v_mov_b32_e32 v10, 0
	v_mov_b32_e32 v11, 0
	v_mov_b32_e32 v12, 0
	v_mov_b32_e32 v13, 0
	v_mov_b32_e32 v14, 0
	v_mov_b32_e32 v15, 0
	v_mov_b32_e32 v16, 0
	v_mov_b32_e32 v17, 0
	v_mov_b32_e32 v18, 0
	v_mov_b32_e32 v19, 0
	v_mov_b32_e32 v20, 0
	v_mov_b32_e32 v21, 0
	v_mov_b32_e32 v22, 0
	v_mov_b32_e32 v23, 0
	v_mov_b32_e32 v24, 0
	v_mov_b32_e32 v25, 0
	v_mov_b32_e32 v26, 0
	v_mov_b32_e32 v27, 0
	v_mov_b32_e32 v28, 0
	v_mov_b32_e32 v29, 0
	v_mov_b32_e32 v30, 0
	v_mov_b32_e32 v31, 0
	global_load_dwordx4 v[32:35], v[150:151], off offset:0
	global_load_dwordx4 v[40:43], v[146:147], off offset:0
	global_load_dwordx4 v[48:51], v[148:149], off offset:0
	global_load_dwordx4 v[36:39], v[150:151], off offset:16
	global_load_dwordx4 v[44:47], v[146:147], off offset:16
	global_load_dwordx4 v[52:55], v[148:149], off offset:16
	global_load_dwordx4 v[56:59], v[150:151], off offset:64
	global_load_dwordx4 v[64:67], v[146:147], off offset:64
	global_load_dwordx4 v[72:75], v[148:149], off offset:64
	global_load_dwordx4 v[60:63], v[150:151], off offset:80
	global_load_dwordx4 v[68:71], v[146:147], off offset:80
	global_load_dwordx4 v[76:79], v[148:149], off offset:80
	global_load_dwordx4 v[80:83], v[150:151], off offset:128
	global_load_dwordx4 v[88:91], v[146:147], off offset:128
	global_load_dwordx4 v[96:99], v[148:149], off offset:128
	global_load_dwordx4 v[84:87], v[150:151], off offset:144
	global_load_dwordx4 v[92:95], v[146:147], off offset:144
	global_load_dwordx4 v[100:103], v[148:149], off offset:144
	global_load_dwordx4 v[104:107], v[150:151], off offset:192
	global_load_dwordx4 v[112:115], v[146:147], off offset:192
	global_load_dwordx4 v[120:123], v[148:149], off offset:192
	global_load_dwordx4 v[108:111], v[150:151], off offset:208
	global_load_dwordx4 v[116:119], v[146:147], off offset:208
	global_load_dwordx4 v[124:127], v[148:149], off offset:208
	s_waitcnt vmcnt(18)
	v_mfma_f32_32x32x16_bf16 v[0:15], v[32:35], v[40:43], v[0:15]
	v_mfma_f32_32x32x16_bf16 v[16:31], v[32:35], v[48:51], v[16:31]
	v_mfma_f32_32x32x16_bf16 v[0:15], v[36:39], v[44:47], v[0:15]
	v_mfma_f32_32x32x16_bf16 v[16:31], v[36:39], v[52:55], v[16:31]
	s_waitcnt vmcnt(12)
	v_mfma_f32_32x32x16_bf16 v[0:15], v[56:59], v[64:67], v[0:15]
	v_mfma_f32_32x32x16_bf16 v[16:31], v[56:59], v[72:75], v[16:31]
	v_mfma_f32_32x32x16_bf16 v[0:15], v[60:63], v[68:71], v[0:15]
	v_mfma_f32_32x32x16_bf16 v[16:31], v[60:63], v[76:79], v[16:31]
	s_waitcnt vmcnt(6)
	v_mfma_f32_32x32x16_bf16 v[0:15], v[80:83], v[88:91], v[0:15]
	v_mfma_f32_32x32x16_bf16 v[16:31], v[80:83], v[96:99], v[16:31]
	v_mfma_f32_32x32x16_bf16 v[0:15], v[84:87], v[92:95], v[0:15]
	v_mfma_f32_32x32x16_bf16 v[16:31], v[84:87], v[100:103], v[16:31]
	s_waitcnt vmcnt(0)
	v_mfma_f32_32x32x16_bf16 v[0:15], v[104:107], v[112:115], v[0:15]
	v_mfma_f32_32x32x16_bf16 v[16:31], v[104:107], v[120:123], v[16:31]
	v_mfma_f32_32x32x16_bf16 v[0:15], v[108:111], v[116:119], v[0:15]
	v_mfma_f32_32x32x16_bf16 v[16:31], v[108:111], v[124:127], v[16:31]
	s_lshl_b32 s7, s4, 13
	v_lshl_add_u32 v152, v140, 4, s7
	s_nop 7
	s_nop 7
	ds_write_b128 v152, v[0:3] offset:0
	ds_write_b128 v152, v[4:7] offset:1024
	ds_write_b128 v152, v[8:11] offset:2048
	ds_write_b128 v152, v[12:15] offset:3072
	ds_write_b128 v152, v[16:19] offset:4096
	ds_write_b128 v152, v[20:23] offset:5120
	ds_write_b128 v152, v[24:27] offset:6144
	ds_write_b128 v152, v[28:31] offset:7168
	s_waitcnt lgkmcnt(0)
	s_barrier
	s_lshl_b32 s7, s4, 10
	v_lshl_add_u32 v152, v140, 4, s7
	ds_read_b128 v[32:35], v152 offset:0
	ds_read_b128 v[36:39], v152 offset:8192
	ds_read_b128 v[40:43], v152 offset:16384
	ds_read_b128 v[44:47], v152 offset:24576
	ds_read_b128 v[48:51], v152 offset:32768
	ds_read_b128 v[52:55], v152 offset:40960
	ds_read_b128 v[56:59], v152 offset:49152
	ds_read_b128 v[60:63], v152 offset:57344
	s_lshr_b32 s8, s4, 2
	s_and_b32 s9, s4, 3
	s_lshl_b32 s8, s8, 5
	s_add_i32 s8, s8, s5
	s_lshl_b32 s9, s9, 3
	s_add_i32 s9, s9, s6
	v_lshl_add_u32 v153, v142, 2, s9
	v_add_u32_e32 v154, s8, v141
	v_lshl_add_u32 v154, v154, 10, v153
	v_lshlrev_b32_e32 v154, 2, v154
	v_lshlrev_b32_e32 v153, 2, v153
	s_add_u32 s10, s2, 0x3100000
	s_addc_u32 s11, s3, 0
	s_add_u32 s12, s2, 0xe000
	s_addc_u32 s13, s3, 0
	global_load_dwordx4 v[64:67], v154, s[10:11]
	global_load_dwordx4 v[68:71], v153, s[12:13]
	s_waitcnt lgkmcnt(0)
	v_add_f32_e32 v32, v32, v36
	v_add_f32_e32 v33, v33, v37
	v_add_f32_e32 v34, v34, v38
	v_add_f32_e32 v35, v35, v39
	v_add_f32_e32 v32, v32, v40
	v_add_f32_e32 v33, v33, v41
	v_add_f32_e32 v34, v34, v42
	v_add_f32_e32 v35, v35, v43
	v_add_f32_e32 v32, v32, v44
	v_add_f32_e32 v33, v33, v45
	v_add_f32_e32 v34, v34, v46
	v_add_f32_e32 v35, v35, v47
	v_add_f32_e32 v32, v32, v48
	v_add_f32_e32 v33, v33, v49
	v_add_f32_e32 v34, v34, v50
	v_add_f32_e32 v35, v35, v51
	v_add_f32_e32 v32, v32, v52
	v_add_f32_e32 v33, v33, v53
	v_add_f32_e32 v34, v34, v54
	v_add_f32_e32 v35, v35, v55
	v_add_f32_e32 v32, v32, v56
	v_add_f32_e32 v33, v33, v57
	v_add_f32_e32 v34, v34, v58
	v_add_f32_e32 v35, v35, v59
	v_add_f32_e32 v32, v32, v60
	v_add_f32_e32 v33, v33, v61
	v_add_f32_e32 v34, v34, v62
	v_add_f32_e32 v35, v35, v63
	s_waitcnt vmcnt(0)
	v_fma_f32 v64, v68, v32, v64
	v_fma_f32 v65, v69, v33, v65
	v_fma_f32 v66, v70, v34, v66
	v_fma_f32 v67, v71, v35, v67
	global_store_dwordx4 v154, v[64:67], s[10:11]
.Lcg_pd_done:
	v_readlane_b32 s0, v248, 0
	v_readlane_b32 s1, v248, 1
	v_readlane_b32 s2, v248, 2
	v_readlane_b32 s3, v248, 3
	v_readlane_b32 s4, v248, 4
	v_readlane_b32 s5, v248, 5
	v_readlane_b32 s6, v248, 6
	v_readlane_b32 s7, v248, 7
	v_readlane_b32 s8, v248, 8
	v_readlane_b32 s9, v248, 9
	v_readlane_b32 s10, v248, 10
	v_readlane_b32 s11, v248, 11
	v_readlane_b32 s12, v248, 12
	v_readlane_b32 s13, v248, 13
	v_readlane_b32 s14, v248, 14
	v_readlane_b32 s15, v248, 15
	v_readlane_b32 s16, v248, 16
	v_readlane_b32 s17, v248, 17
	v_readlane_b32 s18, v248, 18
	v_readlane_b32 s19, v248, 19
	v_readlane_b32 s20, v248, 20
	v_readlane_b32 s21, v248, 21
	v_readlane_b32 s22, v248, 22
	v_readlane_b32 s23, v248, 23
	v_readlane_b32 s24, v248, 24
	v_readlane_b32 s25, v248, 25
	v_readlane_b32 s26, v248, 26
	v_readlane_b32 s27, v248, 27
	s_nop 3
	v_readlane_b32 s0, v251, 20
	v_readlane_b32 s4, v251, 22
	v_readlane_b32 s1, v251, 21
	v_readlane_b32 s5, v251, 23
	s_and_b64 vcc, exec, s[0:1]
	s_mov_b64 s[6:7], 0
	s_cbranch_vccnz .LBB0_699
	v_mbcnt_lo_u32_b32 v0, -1, 0
	v_mbcnt_hi_u32_b32 v0, -1, v0
	s_nop 0
	v_cmp_eq_u32_e32 vcc, 0, v0
	s_and_b64 s[6:7], vcc, exec

.LBB0_943:
	v_writelane_b32 v248, s0, 0
	v_writelane_b32 v248, s1, 1
	v_writelane_b32 v248, s2, 2
	v_writelane_b32 v248, s3, 3
	v_writelane_b32 v248, s4, 4
	v_writelane_b32 v248, s5, 5
	v_writelane_b32 v248, s6, 6
	v_writelane_b32 v248, s7, 7
	v_writelane_b32 v248, s8, 8
	v_writelane_b32 v248, s9, 9
	v_writelane_b32 v248, s10, 10
	v_writelane_b32 v248, s11, 11
	v_writelane_b32 v248, s12, 12
	v_writelane_b32 v248, s13, 13
	v_writelane_b32 v248, s14, 14
	v_writelane_b32 v248, s15, 15
	v_writelane_b32 v248, s16, 16
	v_writelane_b32 v248, s17, 17
	v_writelane_b32 v248, s18, 18
	v_writelane_b32 v248, s19, 19
	v_writelane_b32 v248, s20, 20
	v_writelane_b32 v248, s21, 21
	v_writelane_b32 v248, s22, 22
	v_writelane_b32 v248, s23, 23
	v_writelane_b32 v248, s24, 24
	v_writelane_b32 v248, s25, 25
	v_writelane_b32 v248, s26, 26
	v_writelane_b32 v248, s27, 27
	v_readlane_b32 s0, v254, 38
	v_readlane_b32 s2, v251, 18
	v_readlane_b32 s3, v251, 19
	v_readlane_b32 s4, v251, 44
	s_cmp_lg_u32 s0, 0
	s_cbranch_scc1 .Lcg_ph_done
	s_lshr_b32 s4, s4, 6
	s_lshr_b32 s5, s63, 5
	s_and_b32 s6, s63, 31
	s_lshl_b32 s5, s5, 6
	s_lshl_b32 s6, s6, 5
	v_mbcnt_lo_u32_b32 v140, -1, 0
	v_mbcnt_hi_u32_b32 v140, -1, v140
	v_and_b32_e32 v141, 31, v140
	v_lshrrev_b32_e32 v142, 5, v140
	s_mul_i32 s7, s4, 704
	v_lshl_add_u32 v143, v142, 5, s7
	v_add_u32_e32 v144, s5, v141
	v_mul_u32_u24_e32 v144, 5632, v144
	v_add_u32_e32 v144, v144, v143
	v_mov_b32_e32 v145, 0
	s_add_u32 s8, s2, 0xad00000
	s_addc_u32 s9, s3, 0
	v_lshl_add_u64 v[146:147], s[8:9], 0, v[144:145]
	s_mov_b64 s[10:11], 0x2c000
	v_lshl_add_u64 v[148:149], v[146:147], 0, s[10:11]
	v_add_u32_e32 v144, s6, v141
	v_mul_u32_u24_e32 v144, 5632, v144
	v_add_u32_e32 v144, v144, v143
	s_add_u32 s8, s2, 0x1380000
	s_addc_u32 s9, s3, 0
	v_lshl_add_u64 v[150:151], s[8:9], 0, v[144:145]
	v_mov_b32_e32 v0, 0
	v_mov_b32_e32 v1, 0
	v_mov_b32_e32 v2, 0
	v_mov_b32_e32 v3, 0
	v_mov_b32_e32 v4, 0
	v_mov_b32_e32 v5, 0
	v_mov_b32_e32 v6, 0
	v_mov_b32_e32 v7, 0
	v_mov_b32_e32 v8, 0
	v_mov_b32_e32 v9, 0
	v_mov_b32_e32 v10, 0
	v_mov_b32_e32 v11, 0
	v_mov_b32_e32 v12, 0
	v_mov_b32_e32 v13, 0
	v_mov_b32_e32 v14, 0
	v_mov_b32_e32 v15, 0
	v_mov_b32_e32 v16, 0
	v_mov_b32_e32 v17, 0
	v_mov_b32_e32 v18, 0
	v_mov_b32_e32 v19, 0
	v_mov_b32_e32 v20, 0
	v_mov_b32_e32 v21, 0
	v_mov_b32_e32 v22, 0
	v_mov_b32_e32 v23, 0
	v_mov_b32_e32 v24, 0
	v_mov_b32_e32 v25, 0
	v_mov_b32_e32 v26, 0
	v_mov_b32_e32 v27, 0
	v_mov_b32_e32 v28, 0
	v_mov_b32_e32 v29, 0
	v_mov_b32_e32 v30, 0
	v_mov_b32_e32 v31, 0
	global_load_dwordx4 v[32:35], v[150:151], off offset:0
	global_load_dwordx4 v[40:43], v[146:147], off offset:0
	global_load_dwordx4 v[48:51], v[148:149], off offset:0
	global_load_dwordx4 v[36:39], v[150:151], off offset:16
	global_load_dwordx4 v[44:47], v[146:147], off offset:16
	global_load_dwordx4 v[52:55], v[148:149], off offset:16
	global_load_dwordx4 v[56:59], v[150:151], off offset:64
	global_load_dwordx4 v[64:67], v[146:147], off offset:64
	global_load_dwordx4 v[72:75], v[148:149], off offset:64
	global_load_dwordx4 v[60:63], v[150:151], off offset:80
	global_load_dwordx4 v[68:71], v[146:147], off offset:80
	global_load_dwordx4 v[76:79], v[148:149], off offset:80
	global_load_dwordx4 v[80:83], v[150:151], off offset:128
	global_load_dwordx4 v[88:91], v[146:147], off offset:128
	global_load_dwordx4 v[96:99], v[148:149], off offset:128
	global_load_dwordx4 v[84:87], v[150:151], off offset:144
	global_load_dwordx4 v[92:95], v[146:147], off offset:144
	global_load_dwordx4 v[100:103], v[148:149], off offset:144
	global_load_dwordx4 v[104:107], v[150:151], off offset:192
	global_load_dwordx4 v[112:115], v[146:147], off offset:192
	global_load_dwordx4 v[120:123], v[148:149], off offset:192
	global_load_dwordx4 v[108:111], v[150:151], off offset:208
	global_load_dwordx4 v[116:119], v[146:147], off offset:208
	global_load_dwordx4 v[124:127], v[148:149], off offset:208
	s_waitcnt vmcnt(18)
	v_mfma_f32_32x32x16_bf16 v[0:15], v[32:35], v[40:43], v[0:15]
	v_mfma_f32_32x32x16_bf16 v[16:31], v[32:35], v[48:51], v[16:31]
	v_mfma_f32_32x32x16_bf16 v[0:15], v[36:39], v[44:47], v[0:15]
	v_mfma_f32_32x32x16_bf16 v[16:31], v[36:39], v[52:55], v[16:31]
	global_load_dwordx4 v[32:35], v[150:151], off offset:256
	global_load_dwordx4 v[40:43], v[146:147], off offset:256
	global_load_dwordx4 v[48:51], v[148:149], off offset:256
	global_load_dwordx4 v[36:39], v[150:151], off offset:272
	global_load_dwordx4 v[44:47], v[146:147], off offset:272
	global_load_dwordx4 v[52:55], v[148:149], off offset:272
	s_waitcnt vmcnt(18)
	v_mfma_f32_32x32x16_bf16 v[0:15], v[56:59], v[64:67], v[0:15]
	v_mfma_f32_32x32x16_bf16 v[16:31], v[56:59], v[72:75], v[16:31]
	v_mfma_f32_32x32x16_bf16 v[0:15], v[60:63], v[68:71], v[0:15]
	v_mfma_f32_32x32x16_bf16 v[16:31], v[60:63], v[76:79], v[16:31]
	global_load_dwordx4 v[56:59], v[150:151], off offset:320
	global_load_dwordx4 v[64:67], v[146:147], off offset:320
	global_load_dwordx4 v[72:75], v[148:149], off offset:320
	global_load_dwordx4 v[60:63], v[150:151], off offset:336
	global_load_dwordx4 v[68:71], v[146:147], off offset:336
	global_load_dwordx4 v[76:79], v[148:149], off offset:336
	s_waitcnt vmcnt(18)
	v_mfma_f32_32x32x16_bf16 v[0:15], v[80:83], v[88:91], v[0:15]
	v_mfma_f32_32x32x16_bf16 v[16:31], v[80:83], v[96:99], v[16:31]
	v_mfma_f32_32x32x16_bf16 v[0:15], v[84:87], v[92:95], v[0:15]
	v_mfma_f32_32x32x16_bf16 v[16:31], v[84:87], v[100:103], v[16:31]
	global_load_dwordx4 v[80:83], v[150:151], off offset:384
	global_load_dwordx4 v[88:91], v[146:147], off offset:384
	global_load_dwordx4 v[96:99], v[148:149], off offset:384
	global_load_dwordx4 v[84:87], v[150:151], off offset:400
	global_load_dwordx4 v[92:95], v[146:147], off offset:400
	global_load_dwordx4 v[100:103], v[148:149], off offset:400
	s_waitcnt vmcnt(18)
	v_mfma_f32_32x32x16_bf16 v[0:15], v[104:107], v[112:115], v[0:15]
	v_mfma_f32_32x32x16_bf16 v[16:31], v[104:107], v[120:123], v[16:31]
	v_mfma_f32_32x32x16_bf16 v[0:15], v[108:111], v[116:119], v[0:15]
	v_mfma_f32_32x32x16_bf16 v[16:31], v[108:111], v[124:127], v[16:31]
	global_load_dwordx4 v[104:107], v[150:151], off offset:448
	global_load_dwordx4 v[112:115], v[146:147], off offset:448
	global_load_dwordx4 v[120:123], v[148:149], off offset:448
	global_load_dwordx4 v[108:111], v[150:151], off offset:464
	global_load_dwordx4 v[116:119], v[146:147], off offset:464
	global_load_dwordx4 v[124:127], v[148:149], off offset:464
	s_waitcnt vmcnt(18)
	v_mfma_f32_32x32x16_bf16 v[0:15], v[32:35], v[40:43], v[0:15]
	v_mfma_f32_32x32x16_bf16 v[16:31], v[32:35], v[48:51], v[16:31]
	v_mfma_f32_32x32x16_bf16 v[0:15], v[36:39], v[44:47], v[0:15]
	v_mfma_f32_32x32x16_bf16 v[16:31], v[36:39], v[52:55], v[16:31]
	global_load_dwordx4 v[32:35], v[150:151], off offset:512
	global_load_dwordx4 v[40:43], v[146:147], off offset:512
	global_load_dwordx4 v[48:51], v[148:149], off offset:512
	global_load_dwordx4 v[36:39], v[150:151], off offset:528
	global_load_dwordx4 v[44:47], v[146:147], off offset:528
	global_load_dwordx4 v[52:55], v[148:149], off offset:528
	s_waitcnt vmcnt(18)
	v_mfma_f32_32x32x16_bf16 v[0:15], v[56:59], v[64:67], v[0:15]
	v_mfma_f32_32x32x16_bf16 v[16:31], v[56:59], v[72:75], v[16:31]
	v_mfma_f32_32x32x16_bf16 v[0:15], v[60:63], v[68:71], v[0:15]
	v_mfma_f32_32x32x16_bf16 v[16:31], v[60:63], v[76:79], v[16:31]
	global_load_dwordx4 v[56:59], v[150:151], off offset:576
	global_load_dwordx4 v[64:67], v[146:147], off offset:576
	global_load_dwordx4 v[72:75], v[148:149], off offset:576
	global_load_dwordx4 v[60:63], v[150:151], off offset:592
	global_load_dwordx4 v[68:71], v[146:147], off offset:592
	global_load_dwordx4 v[76:79], v[148:149], off offset:592
	s_waitcnt vmcnt(18)
	v_mfma_f32_32x32x16_bf16 v[0:15], v[80:83], v[88:91], v[0:15]
	v_mfma_f32_32x32x16_bf16 v[16:31], v[80:83], v[96:99], v[16:31]
	v_mfma_f32_32x32x16_bf16 v[0:15], v[84:87], v[92:95], v[0:15]
	v_mfma_f32_32x32x16_bf16 v[16:31], v[84:87], v[100:103], v[16:31]
	global_load_dwordx4 v[80:83], v[150:151], off offset:640
	global_load_dwordx4 v[88:91], v[146:147], off offset:640
	global_load_dwordx4 v[96:99], v[148:149], off offset:640
	global_load_dwordx4 v[84:87], v[150:151], off offset:656
	global_load_dwordx4 v[92:95], v[146:147], off offset:656
	global_load_dwordx4 v[100:103], v[148:149], off offset:656
	s_waitcnt vmcnt(18)
	v_mfma_f32_32x32x16_bf16 v[0:15], v[104:107], v[112:115], v[0:15]
	v_mfma_f32_32x32x16_bf16 v[16:31], v[104:107], v[120:123], v[16:31]
	v_mfma_f32_32x32x16_bf16 v[0:15], v[108:111], v[116:119], v[0:15]
	v_mfma_f32_32x32x16_bf16 v[16:31], v[108:111], v[124:127], v[16:31]
	s_waitcnt vmcnt(12)
	v_mfma_f32_32x32x16_bf16 v[0:15], v[32:35], v[40:43], v[0:15]
	v_mfma_f32_32x32x16_bf16 v[16:31], v[32:35], v[48:51], v[16:31]
	v_mfma_f32_32x32x16_bf16 v[0:15], v[36:39], v[44:47], v[0:15]
	v_mfma_f32_32x32x16_bf16 v[16:31], v[36:39], v[52:55], v[16:31]
	s_waitcnt vmcnt(6)
	v_mfma_f32_32x32x16_bf16 v[0:15], v[56:59], v[64:67], v[0:15]
	v_mfma_f32_32x32x16_bf16 v[16:31], v[56:59], v[72:75], v[16:31]
	v_mfma_f32_32x32x16_bf16 v[0:15], v[60:63], v[68:71], v[0:15]
	v_mfma_f32_32x32x16_bf16 v[16:31], v[60:63], v[76:79], v[16:31]
	s_waitcnt vmcnt(0)
	v_mfma_f32_32x32x16_bf16 v[0:15], v[80:83], v[88:91], v[0:15]
	v_mfma_f32_32x32x16_bf16 v[16:31], v[80:83], v[96:99], v[16:31]
	v_mfma_f32_32x32x16_bf16 v[0:15], v[84:87], v[92:95], v[0:15]
	v_mfma_f32_32x32x16_bf16 v[16:31], v[84:87], v[100:103], v[16:31]
	s_lshl_b32 s7, s4, 13
	v_lshl_add_u32 v152, v140, 4, s7
	s_nop 7
	s_nop 7
	ds_write_b128 v152, v[0:3] offset:0
	ds_write_b128 v152, v[4:7] offset:1024
	ds_write_b128 v152, v[8:11] offset:2048
	ds_write_b128 v152, v[12:15] offset:3072
	ds_write_b128 v152, v[16:19] offset:4096
	ds_write_b128 v152, v[20:23] offset:5120
	ds_write_b128 v152, v[24:27] offset:6144
	ds_write_b128 v152, v[28:31] offset:7168
	s_waitcnt lgkmcnt(0)
	s_barrier
	s_lshl_b32 s7, s4, 10
	v_lshl_add_u32 v152, v140, 4, s7
	ds_read_b128 v[32:35], v152 offset:0
	ds_read_b128 v[36:39], v152 offset:8192
	ds_read_b128 v[40:43], v152 offset:16384
	ds_read_b128 v[44:47], v152 offset:24576
	ds_read_b128 v[48:51], v152 offset:32768
	ds_read_b128 v[52:55], v152 offset:40960
	ds_read_b128 v[56:59], v152 offset:49152
	ds_read_b128 v[60:63], v152 offset:57344
	s_lshr_b32 s8, s4, 2
	s_and_b32 s9, s4, 3
	s_lshl_b32 s8, s8, 5
	s_add_i32 s8, s8, s5
	s_lshl_b32 s9, s9, 3
	s_add_i32 s9, s9, s6
	v_lshl_add_u32 v153, v142, 2, s9
	v_add_u32_e32 v154, s8, v141
	v_lshl_add_u32 v154, v154, 10, v153
	v_lshlrev_b32_e32 v154, 2, v154
	v_lshlrev_b32_e32 v153, 2, v153
	s_add_u32 s10, s2, 0x3100000
	s_addc_u32 s11, s3, 0
	s_add_u32 s12, s2, 0x11000
	s_addc_u32 s13, s3, 0
	global_load_dwordx4 v[64:67], v154, s[10:11]
	global_load_dwordx4 v[68:71], v153, s[12:13]
	s_waitcnt lgkmcnt(0)
	v_add_f32_e32 v32, v32, v36
	v_add_f32_e32 v33, v33, v37
	v_add_f32_e32 v34, v34, v38
	v_add_f32_e32 v35, v35, v39
	v_add_f32_e32 v32, v32, v40
	v_add_f32_e32 v33, v33, v41
	v_add_f32_e32 v34, v34, v42
	v_add_f32_e32 v35, v35, v43
	v_add_f32_e32 v32, v32, v44
	v_add_f32_e32 v33, v33, v45
	v_add_f32_e32 v34, v34, v46
	v_add_f32_e32 v35, v35, v47
	v_add_f32_e32 v32, v32, v48
	v_add_f32_e32 v33, v33, v49
	v_add_f32_e32 v34, v34, v50
	v_add_f32_e32 v35, v35, v51
	v_add_f32_e32 v32, v32, v52
	v_add_f32_e32 v33, v33, v53
	v_add_f32_e32 v34, v34, v54
	v_add_f32_e32 v35, v35, v55
	v_add_f32_e32 v32, v32, v56
	v_add_f32_e32 v33, v33, v57
	v_add_f32_e32 v34, v34, v58
	v_add_f32_e32 v35, v35, v59
	v_add_f32_e32 v32, v32, v60
	v_add_f32_e32 v33, v33, v61
	v_add_f32_e32 v34, v34, v62
	v_add_f32_e32 v35, v35, v63
	s_waitcnt vmcnt(0)
	v_fma_f32 v64, v68, v32, v64
	v_fma_f32 v65, v69, v33, v65
	v_fma_f32 v66, v70, v34, v66
	v_fma_f32 v67, v71, v35, v67
	global_store_dwordx4 v154, v[64:67], s[10:11]
.Lcg_ph_done:
	v_readlane_b32 s0, v248, 0
	v_readlane_b32 s1, v248, 1
	v_readlane_b32 s2, v248, 2
	v_readlane_b32 s3, v248, 3
	v_readlane_b32 s4, v248, 4
	v_readlane_b32 s5, v248, 5
	v_readlane_b32 s6, v248, 6
	v_readlane_b32 s7, v248, 7
	v_readlane_b32 s8, v248, 8
	v_readlane_b32 s9, v248, 9
	v_readlane_b32 s10, v248, 10
	v_readlane_b32 s11, v248, 11
	v_readlane_b32 s12, v248, 12
	v_readlane_b32 s13, v248, 13
	v_readlane_b32 s14, v248, 14
	v_readlane_b32 s15, v248, 15
	v_readlane_b32 s16, v248, 16
	v_readlane_b32 s17, v248, 17
	v_readlane_b32 s18, v248, 18
	v_readlane_b32 s19, v248, 19
	v_readlane_b32 s20, v248, 20
	v_readlane_b32 s21, v248, 21
	v_readlane_b32 s22, v248, 22
	v_readlane_b32 s23, v248, 23
	v_readlane_b32 s24, v248, 24
	v_readlane_b32 s25, v248, 25
	v_readlane_b32 s26, v248, 26
	v_readlane_b32 s27, v248, 27
	s_nop 3
	v_readlane_b32 s0, v254, 59
	v_readlane_b32 s1, v254, 60
	s_andn2_b64 vcc, exec, s[0:1]
	s_cbranch_vccnz .LBB0_146
	v_readlane_b32 s0, v251, 20
	v_readlane_b32 s4, v251, 22
	v_readlane_b32 s1, v251, 21
	v_readlane_b32 s5, v251, 23
	s_and_b64 vcc, exec, s[0:1]
	s_mov_b64 s[6:7], 0
	s_cbranch_vccnz .LBB0_946
	v_mbcnt_lo_u32_b32 v0, -1, 0
	v_mbcnt_hi_u32_b32 v0, -1, v0
	s_nop 0
	v_cmp_eq_u32_e32 vcc, 0, v0
	s_and_b64 s[6:7], vcc, exec
